# DA prio levels: B-wave MFMA cluster 3 (above A-wave QK 2), A softmax 1, B softmax 0
# baseline (speedup 1.0000x reference)
; template <int NC, int DQK, int DV, bool CAUSAL, bool PF> ...
;     ...
;       _Pragma("unroll") for (int ks = 0; ks < NKS; ++ks) _Pragma("unroll") for (int m = 0; m < 4; ++m) {
;         bf16x8 a = *(const bf16x8*)&Kb[(16 * m + fr) * KLD + c * DQK + ks * 32 + fq * 8];
;         s[m] = __builtin_amdgcn_mfma_f32_16x16x32_bf16(a, qf[c][ks], s[m], 0, 0, 0);
;     ...
;     _Pragma("unroll") for (int k2 = 0; k2 < 2; ++k2) _Pragma("unroll") for (int v = 0; v < NVT; ++v) {
;       bf16x8 a = *(const bf16x8*)&Vb[(16 * v + fr) * VLD + 32 * k2 + fq * 8];
;       _Pragma("unroll") for (int c = 0; c < NC; ++c) O[c][v] = __builtin_amdgcn_mfma_f32_16x16x32_bf16(a, pf[c][k2], O[c][v], 0, 0, 0);
;       if ((v & 3) == 3) __builtin_amdgcn_sched_barrier(0);
;     }
.Ldb_fastB:
	s_setprio 3
	v_add3_u32 v172, s38, v32, v195
	s_cmp_eq_u32 s34, 0
	s_cbranch_scc1 .Ldb_B_nopend
	s_sub_i32 s8, s37, 0x5000
	s_cmp_lt_i32 s8, 0
	s_cselect_b32 s8, 0xa000, s8
	v_add3_u32 v173, s8, v32, v193
	ds_read_b128 v[0:3], v173 offset:36864
	ds_read_b128 v[4:7], v173 offset:39424
	ds_read_b128 v[8:11], v173 offset:41984
	ds_read_b128 v[12:15], v173 offset:44544
	ds_read_b128 v[16:19], v173 offset:47104
	ds_read_b128 v[20:23], v173 offset:49664
	ds_read_b128 v[24:27], v173 offset:52224
	ds_read_b128 v[28:31], v173 offset:54784
	ds_read_b128 v[122:125], v173 offset:36928
	ds_read_b128 v[126:129], v173 offset:39488
	ds_read_b128 v[130:133], v173 offset:42048
	ds_read_b128 v[142:145], v173 offset:44608
	s_waitcnt lgkmcnt(10)
	v_mfma_f32_16x16x32_bf16 v[106:109], v[0:3], v[146:149], v[106:109]
	v_mfma_f32_16x16x32_bf16 v[110:113], v[0:3], v[154:157], v[110:113]
	v_mfma_f32_16x16x32_bf16 v[98:101], v[4:7], v[146:149], v[98:101]
	v_mfma_f32_16x16x32_bf16 v[102:105], v[4:7], v[154:157], v[102:105]
	s_waitcnt lgkmcnt(8)
	v_mfma_f32_16x16x32_bf16 v[90:93], v[8:11], v[146:149], v[90:93]
	v_mfma_f32_16x16x32_bf16 v[94:97], v[8:11], v[154:157], v[94:97]
	v_mfma_f32_16x16x32_bf16 v[78:81], v[12:15], v[146:149], v[78:81]
	v_mfma_f32_16x16x32_bf16 v[74:77], v[12:15], v[154:157], v[74:77]
	ds_read_b128 v[0:3], v173 offset:47168
	ds_read_b128 v[4:7], v173 offset:49728
	ds_read_b128 v[8:11], v173 offset:52288
	ds_read_b128 v[12:15], v173 offset:54848
	s_waitcnt lgkmcnt(10)
	v_mfma_f32_16x16x32_bf16 v[62:65], v[16:19], v[146:149], v[62:65]
	v_mfma_f32_16x16x32_bf16 v[70:73], v[16:19], v[154:157], v[70:73]
	v_mfma_f32_16x16x32_bf16 v[50:53], v[20:23], v[146:149], v[50:53]
	v_mfma_f32_16x16x32_bf16 v[66:69], v[20:23], v[154:157], v[66:69]
	s_waitcnt lgkmcnt(8)
	v_mfma_f32_16x16x32_bf16 v[54:57], v[24:27], v[146:149], v[54:57]
	v_mfma_f32_16x16x32_bf16 v[58:61], v[24:27], v[154:157], v[58:61]
	v_mfma_f32_16x16x32_bf16 v[82:85], v[28:31], v[146:149], v[82:85]
	v_mfma_f32_16x16x32_bf16 v[86:89], v[28:31], v[154:157], v[86:89]
	ds_read_b128 v[16:19], v172 offset:64
	ds_read_b128 v[20:23], v172 offset:4672
	ds_read_b128 v[24:27], v172 offset:9280
	ds_read_b128 v[28:31], v172 offset:13888
	s_waitcnt lgkmcnt(10)
	v_mfma_f32_16x16x32_bf16 v[106:109], v[122:125], v[150:153], v[106:109]
	v_mfma_f32_16x16x32_bf16 v[110:113], v[122:125], v[158:161], v[110:113]
	v_mfma_f32_16x16x32_bf16 v[98:101], v[126:129], v[150:153], v[98:101]
	v_mfma_f32_16x16x32_bf16 v[102:105], v[126:129], v[158:161], v[102:105]
	s_waitcnt lgkmcnt(8)
	v_mfma_f32_16x16x32_bf16 v[90:93], v[130:133], v[150:153], v[90:93]
	v_mfma_f32_16x16x32_bf16 v[94:97], v[130:133], v[158:161], v[94:97]
	v_mfma_f32_16x16x32_bf16 v[78:81], v[142:145], v[150:153], v[78:81]
	v_mfma_f32_16x16x32_bf16 v[74:77], v[142:145], v[158:161], v[74:77]
	ds_read_b128 v[122:125], v172
	ds_read_b128 v[126:129], v172 offset:4608
	ds_read_b128 v[130:133], v172 offset:9216
	ds_read_b128 v[142:145], v172 offset:13824
	s_waitcnt lgkmcnt(10)
	v_mfma_f32_16x16x32_bf16 v[62:65], v[0:3], v[150:153], v[62:65]
	v_mfma_f32_16x16x32_bf16 v[70:73], v[0:3], v[158:161], v[70:73]
	v_mfma_f32_16x16x32_bf16 v[50:53], v[4:7], v[150:153], v[50:53]
	v_mfma_f32_16x16x32_bf16 v[66:69], v[4:7], v[158:161], v[66:69]
	s_waitcnt lgkmcnt(8)
	v_mfma_f32_16x16x32_bf16 v[54:57], v[8:11], v[150:153], v[54:57]
	v_mfma_f32_16x16x32_bf16 v[58:61], v[8:11], v[158:161], v[58:61]
	v_mfma_f32_16x16x32_bf16 v[82:85], v[12:15], v[150:153], v[82:85]
	v_mfma_f32_16x16x32_bf16 v[86:89], v[12:15], v[158:161], v[86:89]
	ds_read_b128 v[0:3], v172 offset:128
	ds_read_b128 v[4:7], v172 offset:4736
	ds_read_b128 v[8:11], v172 offset:9344
	ds_read_b128 v[12:15], v172 offset:13952
	s_branch .Ldb_B_qk
